# mLSTM step 3 score tiles: per-row decay vectors read once per tile with two ds_read_b128 before the MFMAs; per-value LDS reads and LDS drain waits removed
# speedup vs baseline: 1.0131x; 1.0064x over previous
.LBB0_228:
	v_or_b32_e32 v74, s58, v73
	v_mul_u32_u24_e32 v75, 0x110, v74
	v_add3_u32 v75, 0, v75, v72
	ds_read_b128 v[64:67], v71
	ds_read_b128 v[76:79], v75 offset:17408
	ds_read_b128 v[84:87], v71 offset:64
	ds_read_b128 v[80:83], v75 offset:17472
	ds_read_b128 v[88:91], v71 offset:128
	ds_read_b128 v[92:95], v75 offset:17536
	ds_read_b128 v[156:159], v71 offset:192
	ds_read_b128 v[160:163], v75 offset:17600
	v_cmp_le_u32_e32 vcc, v74, v70
	v_lshl_add_u32 v75, v74, 2, 0
	v_add_u32_e32 v75, 0x20900, v75
	ds_read_b32 v75, v75
	v_lshlrev_b32_e32 v184, 2, v70
	v_add_u32_e32 v184, 0x20800, v184
	ds_read_b128 v[172:175], v184
	ds_read_b128 v[180:183], v184 offset:512
	s_waitcnt lgkmcnt(9)
	v_mfma_f32_16x16x32_bf16 v[64:67], v[64:67], v[76:79], 0
	s_waitcnt lgkmcnt(7)
	v_mfma_f32_16x16x32_bf16 v[64:67], v[84:87], v[80:83], v[64:67]
	s_waitcnt lgkmcnt(5)
	v_mfma_f32_16x16x32_bf16 v[64:67], v[88:91], v[92:95], v[64:67]
	s_waitcnt lgkmcnt(3)
	v_mfma_f32_16x16x32_bf16 v[64:67], v[156:159], v[160:163], v[64:67]
	s_waitcnt lgkmcnt(0)
	s_nop 7
	v_mov_b32_e32 v76, 0
	s_and_saveexec_b64 s[12:13], vcc
	s_cbranch_execz .LBB0_230
	v_lshl_add_u32 v76, v70, 2, 0
	v_add_u32_e32 v77, 0x20800, v76
	v_add_u32_e32 v76, 0x20a00, v76
	v_mov_b32_e32 v77, v172
	v_mov_b32_e32 v76, v180
	v_add_f32_e32 v77, v75, v77
	v_sub_f32_e32 v76, v77, v76
	v_mul_f32_e32 v76, 0x3fb8aa3b, v76
	v_exp_f32_e32 v76, v76
	s_nop 0
	v_mul_f32_e32 v76, v64, v76
.LBB0_230:
	s_or_b64 exec, exec, s[12:13]
	s_nop 3
	v_lshl_add_u32 v64, v74, 1, s15
	v_mul_lo_u32 v78, v70, s93
	v_cvt_pk_bf16_f32 v77, v76, s0
	v_add_u32_e32 v64, v64, v78
	ds_write_b16 v64, v77
	s_nop 1
	v_add_f32_dpp v76, v76, v76 quad_perm:[1,0,3,2] row_mask:0xf bank_mask:0xf
	s_nop 1
	v_add_f32_dpp v76, v76, v76 quad_perm:[2,3,0,1] row_mask:0xf bank_mask:0xf
	s_nop 1
	v_add_f32_dpp v76, v76, v76 row_half_mirror row_mask:0xf bank_mask:0xf
	s_nop 1
	v_mov_b32_dpp v77, v76 row_ror:8 row_mask:0xf bank_mask:0xf
	s_and_saveexec_b64 s[12:13], s[42:43]
	s_cbranch_execz .LBB0_232
	v_add_f32_e32 v76, v76, v77
	v_lshl_add_u32 v77, v70, 2, 0
	v_add_u32_e32 v77, 0x20e00, v77
	ds_add_f32 v77, v76
.LBB0_232:
	s_or_b64 exec, exec, s[12:13]
	v_or_b32_e32 v76, 1, v70
	v_cmp_le_u32_e32 vcc, v74, v76
	v_mov_b32_e32 v77, 0
	v_lshl_add_u32 v76, v76, 2, 0
	s_and_saveexec_b64 s[12:13], vcc
	s_cbranch_execz .LBB0_234
	v_add_u32_e32 v77, 0x20800, v76
	v_add_u32_e32 v78, 0x20a00, v76
	v_mov_b32_e32 v77, v173
	v_mov_b32_e32 v78, v181
	v_add_f32_e32 v77, v75, v77
	v_sub_f32_e32 v77, v77, v78
	v_mul_f32_e32 v77, 0x3fb8aa3b, v77
	v_exp_f32_e32 v77, v77
	s_nop 0
	v_mul_f32_e32 v77, v65, v77
.LBB0_234:
	s_or_b64 exec, exec, s[12:13]
	v_cvt_pk_bf16_f32 v65, v77, s0
	ds_write_b16 v64, v65 offset:144
	s_nop 1
	v_add_f32_dpp v65, v77, v77 quad_perm:[1,0,3,2] row_mask:0xf bank_mask:0xf
	s_nop 1
	v_add_f32_dpp v65, v65, v65 quad_perm:[2,3,0,1] row_mask:0xf bank_mask:0xf
	s_nop 1
	v_add_f32_dpp v65, v65, v65 row_half_mirror row_mask:0xf bank_mask:0xf
	s_nop 1
	v_mov_b32_dpp v77, v65 row_ror:8 row_mask:0xf bank_mask:0xf
	s_and_saveexec_b64 s[12:13], s[42:43]
	s_cbranch_execz .LBB0_236
	v_add_f32_e32 v65, v65, v77
	v_add_u32_e32 v76, 0x20e00, v76
	ds_add_f32 v76, v65
.LBB0_236:
	s_or_b64 exec, exec, s[12:13]
	v_or_b32_e32 v65, 2, v70
	v_cmp_le_u32_e32 vcc, v74, v65
	v_mov_b32_e32 v76, 0
	v_lshl_add_u32 v65, v65, 2, 0
	s_and_saveexec_b64 s[12:13], vcc
	s_cbranch_execz .LBB0_238
	v_add_u32_e32 v76, 0x20800, v65
	v_add_u32_e32 v77, 0x20a00, v65
	v_mov_b32_e32 v76, v174
	v_mov_b32_e32 v77, v182
	v_add_f32_e32 v76, v75, v76
	v_sub_f32_e32 v76, v76, v77
	v_mul_f32_e32 v76, 0x3fb8aa3b, v76
	v_exp_f32_e32 v76, v76
	s_nop 0
	v_mul_f32_e32 v76, v66, v76
.LBB0_238:
	s_or_b64 exec, exec, s[12:13]
	v_cvt_pk_bf16_f32 v66, v76, s0
	ds_write_b16 v64, v66 offset:288
	s_nop 1
	v_add_f32_dpp v66, v76, v76 quad_perm:[1,0,3,2] row_mask:0xf bank_mask:0xf
	s_nop 1
	v_add_f32_dpp v66, v66, v66 quad_perm:[2,3,0,1] row_mask:0xf bank_mask:0xf
	s_nop 1
	v_add_f32_dpp v66, v66, v66 row_half_mirror row_mask:0xf bank_mask:0xf
	s_nop 1
	v_mov_b32_dpp v76, v66 row_ror:8 row_mask:0xf bank_mask:0xf
	s_and_saveexec_b64 s[12:13], s[42:43]
	s_cbranch_execz .LBB0_240
	v_add_f32_e32 v66, v66, v76
	v_add_u32_e32 v65, 0x20e00, v65
	ds_add_f32 v65, v66
.LBB0_240:
	s_or_b64 exec, exec, s[12:13]
	v_or_b32_e32 v65, 3, v70
	v_cmp_le_u32_e32 vcc, v74, v65
	v_mov_b32_e32 v66, 0
	v_lshl_add_u32 v65, v65, 2, 0
	s_and_saveexec_b64 s[12:13], vcc
	s_cbranch_execz .LBB0_242
	v_add_u32_e32 v66, 0x20800, v65
	v_mov_b32_e32 v66, v175
	v_add_u32_e32 v74, 0x20a00, v65
	v_mov_b32_e32 v74, v183
	v_add_f32_e32 v66, v75, v66
	v_sub_f32_e32 v66, v66, v74
	v_mul_f32_e32 v66, 0x3fb8aa3b, v66
	v_exp_f32_e32 v66, v66
	s_nop 0
	v_mul_f32_e32 v66, v67, v66
.LBB0_242:
	s_or_b64 exec, exec, s[12:13]
	v_cvt_pk_bf16_f32 v67, v66, s0
	ds_write_b16 v64, v67 offset:432
	s_nop 1
	v_add_f32_dpp v64, v66, v66 quad_perm:[1,0,3,2] row_mask:0xf bank_mask:0xf
	s_nop 1
	v_add_f32_dpp v64, v64, v64 quad_perm:[2,3,0,1] row_mask:0xf bank_mask:0xf
	s_nop 1
	v_add_f32_dpp v64, v64, v64 row_half_mirror row_mask:0xf bank_mask:0xf
	s_nop 1
	v_mov_b32_dpp v66, v64 row_ror:8 row_mask:0xf bank_mask:0xf
	s_and_saveexec_b64 s[12:13], s[42:43]
	s_cbranch_execz .LBB0_244
	v_add_f32_e32 v64, v64, v66
	v_add_u32_e32 v65, 0x20e00, v65
	ds_add_f32 v65, v64

.LBB0_247:
	s_waitcnt lgkmcnt(0)
	v_or_b32_e32 v73, s97, v73
	v_mul_u32_u24_e32 v75, 0x110, v73
	v_add3_u32 v72, 0, v75, v72
	ds_read_b128 v[64:67], v71
	ds_read_b128 v[76:79], v72 offset:17408
	ds_read_b128 v[84:87], v71 offset:64
	ds_read_b128 v[80:83], v72 offset:17472
	ds_read_b128 v[88:91], v71 offset:128
	ds_read_b128 v[92:95], v72 offset:17536
	ds_read_b128 v[156:159], v71 offset:192
	ds_read_b128 v[160:163], v72 offset:17600
	v_cmp_le_u32_e32 vcc, v73, v70
	v_mov_b32_e32 v75, 0
	v_lshl_add_u32 v71, v73, 2, 0
	v_add_u32_e32 v71, 0x20900, v71
	ds_read_b32 v71, v71
	v_lshlrev_b32_e32 v184, 2, v70
	v_add_u32_e32 v184, 0x20800, v184
	ds_read_b128 v[172:175], v184
	ds_read_b128 v[180:183], v184 offset:512
	s_waitcnt lgkmcnt(9)
	v_mfma_f32_16x16x32_bf16 v[64:67], v[64:67], v[76:79], 0
	s_waitcnt lgkmcnt(7)
	v_mfma_f32_16x16x32_bf16 v[64:67], v[84:87], v[80:83], v[64:67]
	s_waitcnt lgkmcnt(5)
	v_mfma_f32_16x16x32_bf16 v[64:67], v[88:91], v[92:95], v[64:67]
	s_waitcnt lgkmcnt(3)
	v_mfma_f32_16x16x32_bf16 v[64:67], v[156:159], v[160:163], v[64:67]
	s_waitcnt lgkmcnt(0)
	s_nop 7
	v_lshl_add_u32 v72, v70, 2, 0
	s_and_saveexec_b64 s[12:13], vcc
	s_cbranch_execz .LBB0_249
	v_add_u32_e32 v75, 0x20800, v72
	v_add_u32_e32 v76, 0x20a00, v72
	v_mov_b32_e32 v75, v172
	v_mov_b32_e32 v76, v180
	v_add_f32_e32 v75, v71, v75
	v_sub_f32_e32 v75, v75, v76
	v_mul_f32_e32 v75, 0x3fb8aa3b, v75
	v_exp_f32_e32 v75, v75
	s_nop 0
	v_mul_f32_e32 v75, v64, v75
.LBB0_249:
	s_or_b64 exec, exec, s[12:13]
	s_nop 3
	v_lshl_add_u32 v64, v73, 1, s15
	v_add_u32_e32 v64, v64, v74
	v_cvt_pk_bf16_f32 v76, v75, s0
	ds_write_b16 v64, v76
	s_nop 1
	v_add_f32_dpp v74, v75, v75 quad_perm:[1,0,3,2] row_mask:0xf bank_mask:0xf
	s_nop 1
	v_add_f32_dpp v74, v74, v74 quad_perm:[2,3,0,1] row_mask:0xf bank_mask:0xf
	s_nop 1
	v_add_f32_dpp v74, v74, v74 row_half_mirror row_mask:0xf bank_mask:0xf
	s_nop 1
	v_mov_b32_dpp v75, v74 row_ror:8 row_mask:0xf bank_mask:0xf
	s_and_saveexec_b64 s[12:13], s[42:43]
	s_cbranch_execz .LBB0_251
	v_add_f32_e32 v74, v74, v75
	v_add_u32_e32 v72, 0x20e00, v72
	ds_add_f32 v72, v74
.LBB0_251:
	s_or_b64 exec, exec, s[12:13]
	v_or_b32_e32 v72, 1, v70
	v_cmp_le_u32_e32 vcc, v73, v72
	v_mov_b32_e32 v74, 0
	v_lshl_add_u32 v72, v72, 2, 0
	s_and_saveexec_b64 s[12:13], vcc
	s_cbranch_execz .LBB0_253
	v_add_u32_e32 v74, 0x20800, v72
	v_add_u32_e32 v75, 0x20a00, v72
	v_mov_b32_e32 v74, v173
	v_mov_b32_e32 v75, v181
	v_add_f32_e32 v74, v71, v74
	v_sub_f32_e32 v74, v74, v75
	v_mul_f32_e32 v74, 0x3fb8aa3b, v74
	v_exp_f32_e32 v74, v74
	s_nop 0
	v_mul_f32_e32 v74, v65, v74
.LBB0_253:
	s_or_b64 exec, exec, s[12:13]
	v_cvt_pk_bf16_f32 v65, v74, s0
	ds_write_b16 v64, v65 offset:144
	s_nop 1
	v_add_f32_dpp v65, v74, v74 quad_perm:[1,0,3,2] row_mask:0xf bank_mask:0xf
	s_nop 1
	v_add_f32_dpp v65, v65, v65 quad_perm:[2,3,0,1] row_mask:0xf bank_mask:0xf
	s_nop 1
	v_add_f32_dpp v65, v65, v65 row_half_mirror row_mask:0xf bank_mask:0xf
	s_nop 1
	v_mov_b32_dpp v74, v65 row_ror:8 row_mask:0xf bank_mask:0xf
	s_and_saveexec_b64 s[12:13], s[42:43]
	s_cbranch_execz .LBB0_255
	v_add_f32_e32 v65, v65, v74
	v_add_u32_e32 v72, 0x20e00, v72
	ds_add_f32 v72, v65
.LBB0_255:
	s_or_b64 exec, exec, s[12:13]
	v_or_b32_e32 v65, 2, v70
	v_cmp_le_u32_e32 vcc, v73, v65
	v_mov_b32_e32 v72, 0
	v_lshl_add_u32 v65, v65, 2, 0
	s_and_saveexec_b64 s[12:13], vcc
	s_cbranch_execz .LBB0_257
	v_add_u32_e32 v72, 0x20800, v65
	v_add_u32_e32 v74, 0x20a00, v65
	v_mov_b32_e32 v72, v174
	v_mov_b32_e32 v74, v182
	v_add_f32_e32 v72, v71, v72
	v_sub_f32_e32 v72, v72, v74
	v_mul_f32_e32 v72, 0x3fb8aa3b, v72
	v_exp_f32_e32 v72, v72
	s_nop 0
	v_mul_f32_e32 v72, v66, v72
.LBB0_257:
	s_or_b64 exec, exec, s[12:13]
	v_cvt_pk_bf16_f32 v66, v72, s0
	ds_write_b16 v64, v66 offset:288
	s_nop 1
	v_add_f32_dpp v66, v72, v72 quad_perm:[1,0,3,2] row_mask:0xf bank_mask:0xf
	s_nop 1
	v_add_f32_dpp v66, v66, v66 quad_perm:[2,3,0,1] row_mask:0xf bank_mask:0xf
	s_nop 1
	v_add_f32_dpp v66, v66, v66 row_half_mirror row_mask:0xf bank_mask:0xf
	s_nop 1
	v_mov_b32_dpp v72, v66 row_ror:8 row_mask:0xf bank_mask:0xf
	s_and_saveexec_b64 s[12:13], s[42:43]
	s_cbranch_execz .LBB0_259
	v_add_f32_e32 v66, v66, v72
	v_add_u32_e32 v65, 0x20e00, v65
	ds_add_f32 v65, v66
.LBB0_259:
	s_or_b64 exec, exec, s[12:13]
	v_or_b32_e32 v65, 3, v70
	v_cmp_le_u32_e32 vcc, v73, v65
	v_mov_b32_e32 v66, 0
	v_lshl_add_u32 v65, v65, 2, 0
	s_and_saveexec_b64 s[12:13], vcc
	s_cbranch_execz .LBB0_261
	v_add_u32_e32 v66, 0x20800, v65
	v_mov_b32_e32 v66, v175
	v_add_u32_e32 v70, 0x20a00, v65
	v_mov_b32_e32 v70, v183
	v_add_f32_e32 v66, v71, v66
	v_sub_f32_e32 v66, v66, v70
	v_mul_f32_e32 v66, 0x3fb8aa3b, v66
	v_exp_f32_e32 v66, v66
	s_nop 0
	v_mul_f32_e32 v66, v67, v66
